# v39 + no-op LDS waits removed from the Up epilogue + shift/mask fast path for the tile-index division in the Up tile header
# speedup vs baseline: 1.0127x; 1.0066x over previous
;     __host__ __device__ bool next(int i, Unit& u) const {
;         const long L = (long)i * G + c; if (L >= nwg) return false;
;         int wgid = (int)L; { const int q = nwg / NXCD, r = nwg % NXCD, xcd = wgid % NXCD, off = wgid / NXCD; wgid = (xcd < r ? xcd * (q + 1) : r * (q + 1) + (xcd - r) * q) + off; }
;         const int nig = WGM * nN, gid = wgid / nig, fm = gid * WGM, gsz = (nM - fm) < WGM ? (nM - fm) : WGM;
;         u.pm = fm + ((wgid % nig) % gsz); u.pn = (wgid % nig) / gsz; return true;
;     }
.LBB0_370:
	s_add_i32 s72, s72, 1
	s_mul_i32 s23, s72, s13
	s_mul_hi_u32 s26, s72, s3
	s_add_i32 s23, s26, s23
	s_mul_i32 s26, s72, s3
	v_readlane_b32 s27, v251, 0
	s_add_u32 s26, s26, s27
	s_addc_u32 s27, s23, s58
	v_mov_b64_e32 v[0:1], 0xb00
	v_cmp_gt_i64_e32 vcc, s[26:27], v[202:203]
	v_cmp_lt_i64_e64 s[36:37], s[26:27], v[0:1]
	s_cbranch_vccnz .LBB0_372
	s_ashr_i32 s22, s26, 31
	s_lshr_b32 s22, s22, 29
	s_add_i32 s22, s26, s22
	s_ashr_i32 s23, s22, 3
	s_and_b32 s22, s22, -8
	s_sub_i32 s22, s26, s22
	s_cmp_lt_i32 s22, 0
	s_movk_i32 s26, 0x161
	s_cselect_b32 s26, s26, 0x160
	s_mul_i32 s22, s22, s26
	s_add_i32 s22, s22, s23
	s_mul_hi_i32 s23, s22, 0x2e8ba2e9
	s_lshr_b32 s26, s23, 31
	s_ashr_i32 s23, s23, 5
	s_add_i32 s23, s23, s26
	s_lshl_b32 s26, s23, 3
	s_sub_i32 s27, 0x80, s26
	s_min_i32 s27, s27, 8
	s_mulk_i32 s23, 0xb0
	s_sub_i32 s23, s22, s23
	s_cmp_eq_u32 s27, 8
	s_cbranch_scc1 .Lfastdiv_up
	s_abs_i32 s40, s27
	v_cvt_f32_u32_e32 v0, s40
	s_sub_i32 s42, 0, s40
	v_rcp_iflag_f32_e32 v0, v0
	s_abs_i32 s22, s23
	s_xor_b32 s41, s23, s27
	s_ashr_i32 s41, s41, 31
	v_mul_f32_e32 v0, 0x4f7ffffe, v0
	v_cvt_u32_f32_e32 v0, v0
	s_nop 0
	v_readfirstlane_b32 s43, v0
	s_mul_i32 s42, s42, s43
	s_mul_hi_u32 s42, s43, s42
	s_add_i32 s43, s43, s42
	s_mul_hi_u32 s42, s22, s43
	s_mul_i32 s43, s42, s40
	s_sub_i32 s22, s22, s43
	s_add_i32 s44, s42, 1
	s_sub_i32 s43, s22, s40
	s_cmp_ge_u32 s22, s40
	s_cselect_b32 s42, s44, s42
	s_cselect_b32 s22, s43, s22
	s_add_i32 s43, s42, 1
	s_cmp_ge_u32 s22, s40
	s_cselect_b32 s22, s43, s42
	s_xor_b32 s22, s22, s41
	s_sub_i32 s22, s22, s41
	s_mul_i32 s27, s22, s27
	s_sub_i32 s23, s23, s27
	s_add_i32 s40, s26, s23
	s_branch .LBB0_372
.Lfastdiv_up:
	s_ashr_i32 s22, s23, 3
	s_and_b32 s23, s23, 7
	s_add_i32 s40, s26, s23

; __device__ __forceinline__ unsigned cvt_pk_bf16(float lo, float hi) { unsigned r; asm volatile("v_cvt_pk_bf16_f32 %0, %1, %2" : "=v"(r) : "v"(lo), "v"(hi)); return r; }
; __device__ __forceinline__ int lane_id_v() { int l; asm volatile("v_mbcnt_lo_u32_b32 %0, -1, 0\n\tv_mbcnt_hi_u32_b32 %0, -1, %0" : "=v"(l)); return l; }
; #define LAS __attribute__((address_space(3)))
;     __device__ __forceinline__ void operator()(const f32x4 (&acc)[2][2][4][2], const pg8::Unit& u, int wr, int wc, int fr_, int fq_) const {
;         const int lane_ = pg8::lane_id_v(); const int fr = lane_ & 15, fq = lane_ >> 4;
;         const int lrow0 = u.pm * 256 + wr * 64 + fr;
;         const int b = batch_of(rowbase + u.pm * 256);
;         f32x4 sv[2][2];
; #pragma unroll
;         for (int bj = 0; bj < 2; ++bj)
; #pragma unroll
;             for (int n = 0; n < 2; ++n) sv[bj][n] = *(const LAS f32x4*)(xl + 16384 + (bj * 128 + wc * 32 + 8 * fq + 4 * n) * 4);
;         float rs8[8]; rows_rstd8_lds(xl, wr * 64 + fr, fq, rs8);
;         const int hcol = u.pn * 128 + wc * 32 + 8 * fq;
; #pragma unroll
;         for (int ai = 0; ai < 2; ++ai)
; #pragma unroll
;             for (int m = 0; m < 4; ++m) {
;                 const int lr = lrow0 + ai * 128 + m * 16;
;                 const float rs = rs8[ai * 4 + m];
;                 const f32x4 g0 = acc[ai][0][m][0] * rs + sv[0][0], g1 = acc[ai][0][m][1] * rs + sv[0][1];
;                 const f32x4 u0 = acc[ai][1][m][0] * rs + sv[1][0], u1 = acc[ai][1][m][1] * rs + sv[1][1];
;                 const f32x2 ha = pg8::silu_mul_pk((f32x2){g0[0], g0[1]}, (f32x2){u0[0], u0[1]}), hb = pg8::silu_mul_pk((f32x2){g0[2], g0[3]}, (f32x2){u0[2], u0[3]});
;                 const f32x2 hc = pg8::silu_mul_pk((f32x2){g1[0], g1[1]}, (f32x2){u1[0], u1[1]}), hd = pg8::silu_mul_pk((f32x2){g1[2], g1[3]}, (f32x2){u1[2], u1[3]});
;                 u32x4 w; w.x = cvt_pk_bf16(ha.x, ha.y); w.y = cvt_pk_bf16(hb.x, hb.y); w.z = cvt_pk_bf16(hc.x, hc.y); w.w = cvt_pk_bf16(hd.x, hd.y);
.LBB0_379:
	v_mbcnt_lo_u32_b32 v228, -1, 0
	v_mbcnt_hi_u32_b32 v228, -1, v228
	v_and_b32_e32 v224, 15, v228
	v_add_u32_e32 v224, s91, v224
	v_lshlrev_b32_e32 v224, 2, v224
	v_add_u32_e32 v224, 0x26800, v224
	ds_read_b32 v208, v224
	ds_read_b32 v209, v224 offset:64
	ds_read_b32 v210, v224 offset:128
	ds_read_b32 v211, v224 offset:192
	ds_read_b32 v212, v224 offset:512
	ds_read_b32 v213, v224 offset:576
	ds_read_b32 v214, v224 offset:640
	ds_read_b32 v215, v224 offset:704
	v_mbcnt_lo_u32_b32 v158, -1, 0
	v_mbcnt_hi_u32_b32 v158, -1, v158
	s_add_i32 s23, s23, s91
	v_and_b32_e32 v159, 15, v158
	v_or_b32_e32 v165, s23, v159
	v_ashrrev_i32_e32 v167, 4, v158
	v_readlane_b32 s26, v252, 22
	s_add_i32 s23, 0, 0x22400
	v_lshl_add_u32 v80, v167, 5, s26
	ds_read_b128 v[92:95], v80
	ds_read_b128 v[88:91], v80 offset:16
	ds_read_b128 v[84:87], v80 offset:512
	ds_read_b128 v[80:83], v80 offset:528
	s_mov_b32 s26, 0x358637bd
	s_lshl_b32 s2, s2, 7
	s_waitcnt lgkmcnt(0)
	s_or_b32 s2, s2, s15
	s_mov_b64 s[76:77], s[62:63]
	s_nop 0
	s_nop 0
	s_nop 0
	v_mov_b32_e32 v172, v208
	v_mov_b32_e32 v170, v209
	v_pk_fma_f32 v[126:127], v[126:127], v[170:171], v[94:95] op_sel_hi:[1,0,1]
	v_pk_fma_f32 v[124:125], v[124:125], v[170:171], v[92:93] op_sel_hi:[1,0,1]
	v_pk_fma_f32 v[116:117], v[116:117], v[170:171], v[84:85] op_sel_hi:[1,0,1]
	v_pk_fma_f32 v[118:119], v[118:119], v[170:171], v[86:87] op_sel_hi:[1,0,1]
	v_pk_mul_f32 v[116:117], v[124:125], v[116:117]
	v_pk_fma_f32 v[120:121], v[120:121], v[170:171], v[88:89] op_sel_hi:[1,0,1]
	v_pk_mul_f32 v[118:119], v[126:127], v[118:119]
	v_pk_fma_f32 v[112:113], v[112:113], v[170:171], v[80:81] op_sel_hi:[1,0,1]
	v_pk_fma_f32 v[122:123], v[122:123], v[170:171], v[90:91] op_sel_hi:[1,0,1]
	v_pk_mul_f32 v[112:113], v[120:121], v[112:113]
	v_pk_fma_f32 v[114:115], v[114:115], v[170:171], v[82:83] op_sel_hi:[1,0,1]
	v_pk_mul_f32 v[114:115], v[122:123], v[114:115]
	s_nop 0
	s_nop 0
	v_mov_b32_e32 v168, v210
	v_pk_fma_f32 v[110:111], v[110:111], v[168:169], v[94:95] op_sel_hi:[1,0,1]
	v_pk_fma_f32 v[108:109], v[108:109], v[168:169], v[92:93] op_sel_hi:[1,0,1]
	v_pk_fma_f32 v[100:101], v[100:101], v[168:169], v[84:85] op_sel_hi:[1,0,1]
	v_mov_b32_e32 v166, v211
	v_pk_mul_f32 v[100:101], v[108:109], v[100:101]
	v_pk_fma_f32 v[102:103], v[102:103], v[168:169], v[86:87] op_sel_hi:[1,0,1]
	v_pk_fma_f32 v[104:105], v[104:105], v[168:169], v[88:89] op_sel_hi:[1,0,1]
	v_pk_mul_f32 v[102:103], v[110:111], v[102:103]
	v_pk_fma_f32 v[96:97], v[96:97], v[168:169], v[80:81] op_sel_hi:[1,0,1]
	v_pk_fma_f32 v[106:107], v[106:107], v[168:169], v[90:91] op_sel_hi:[1,0,1]
	v_pk_mul_f32 v[96:97], v[104:105], v[96:97]
	v_pk_fma_f32 v[98:99], v[98:99], v[168:169], v[82:83] op_sel_hi:[1,0,1]
	v_pk_fma_f32 v[78:79], v[78:79], v[166:167], v[94:95] op_sel_hi:[1,0,1]
	v_pk_mul_f32 v[98:99], v[106:107], v[98:99]
	v_pk_fma_f32 v[76:77], v[76:77], v[166:167], v[92:93] op_sel_hi:[1,0,1]
	v_pk_fma_f32 v[68:69], v[68:69], v[166:167], v[84:85] op_sel_hi:[1,0,1]
	v_pk_mul_f32 v[68:69], v[76:77], v[68:69]
	v_pk_fma_f32 v[70:71], v[70:71], v[166:167], v[86:87] op_sel_hi:[1,0,1]
	v_pk_fma_f32 v[72:73], v[72:73], v[166:167], v[88:89] op_sel_hi:[1,0,1]
	v_pk_mul_f32 v[70:71], v[78:79], v[70:71]
	v_mov_b32_e32 v164, v212
	v_pk_fma_f32 v[64:65], v[64:65], v[166:167], v[80:81] op_sel_hi:[1,0,1]
	v_pk_fma_f32 v[74:75], v[74:75], v[166:167], v[90:91] op_sel_hi:[1,0,1]
	v_pk_mul_f32 v[64:65], v[72:73], v[64:65]
	v_pk_fma_f32 v[142:143], v[142:143], v[172:173], v[94:95] op_sel_hi:[1,0,1]
	v_pk_fma_f32 v[140:141], v[140:141], v[172:173], v[92:93] op_sel_hi:[1,0,1]
	v_pk_fma_f32 v[132:133], v[132:133], v[172:173], v[84:85] op_sel_hi:[1,0,1]
	v_mov_b32_e32 v162, v213
	v_pk_fma_f32 v[138:139], v[138:139], v[172:173], v[90:91] op_sel_hi:[1,0,1]
	v_pk_fma_f32 v[136:137], v[136:137], v[172:173], v[88:89] op_sel_hi:[1,0,1]
	v_pk_fma_f32 v[134:135], v[134:135], v[172:173], v[86:87] op_sel_hi:[1,0,1]
	v_pk_fma_f32 v[128:129], v[128:129], v[172:173], v[80:81] op_sel_hi:[1,0,1]
	v_pk_fma_f32 v[130:131], v[130:131], v[172:173], v[82:83] op_sel_hi:[1,0,1]
	v_pk_mul_f32 v[172:173], v[140:141], s[88:89] op_sel_hi:[1,0]
	v_pk_mul_f32 v[132:133], v[140:141], v[132:133]
	v_pk_mul_f32 v[140:141], v[142:143], s[88:89] op_sel_hi:[1,0]
	v_exp_f32_e32 v140, v140
	v_exp_f32_e32 v141, v141
	s_nop 0
	v_pk_add_f32 v[140:141], v[140:141], 1.0 op_sel_hi:[1,0]
	v_rcp_f32_e32 v140, v140
	v_rcp_f32_e32 v141, v141
	v_pk_mul_f32 v[134:135], v[142:143], v[134:135]
	v_exp_f32_e32 v172, v172
	v_pk_mul_f32 v[134:135], v[134:135], v[140:141]
	v_pk_mul_f32 v[140:141], v[136:137], s[88:89] op_sel_hi:[1,0]
	v_exp_f32_e32 v173, v173
	v_exp_f32_e32 v140, v140
	v_exp_f32_e32 v141, v141
	v_pk_mul_f32 v[128:129], v[136:137], v[128:129]
	v_pk_mul_f32 v[136:137], v[138:139], s[88:89] op_sel_hi:[1,0]
	v_exp_f32_e32 v136, v136
	v_exp_f32_e32 v137, v137
	v_pk_add_f32 v[172:173], v[172:173], 1.0 op_sel_hi:[1,0]
	v_pk_add_f32 v[140:141], v[140:141], 1.0 op_sel_hi:[1,0]
	v_rcp_f32_e32 v172, v172
	v_rcp_f32_e32 v173, v173
	v_rcp_f32_e32 v140, v140
	v_rcp_f32_e32 v141, v141
	v_pk_add_f32 v[136:137], v[136:137], 1.0 op_sel_hi:[1,0]
	v_rcp_f32_e32 v136, v136
	v_rcp_f32_e32 v137, v137
	v_lshl_add_u32 v174, v167, 3, s2
	v_pk_mul_f32 v[132:133], v[132:133], v[172:173]
	v_pk_mul_f32 v[130:131], v[138:139], v[130:131]
	v_pk_mul_f32 v[128:129], v[128:129], v[140:141]
	v_ashrrev_i32_e32 v175, 31, v174
	v_pk_mul_f32 v[130:131], v[130:131], v[136:137]
	v_cvt_pk_bf16_f32 v132, v132, v133
	v_cvt_pk_bf16_f32 v133, v134, v135
	v_cvt_pk_bf16_f32 v134, v128, v129
	v_mov_b64_e32 v[128:129], s[30:31]
	s_movk_i32 s2, 0x1600
	v_cvt_pk_bf16_f32 v135, v130, v131
; __device__ __forceinline__ unsigned cvt_pk_bf16(float lo, float hi) { unsigned r; asm volatile("v_cvt_pk_bf16_f32 %0, %1, %2" : "=v"(r) : "v"(lo), "v"(hi)); return r; }
;     __device__ __forceinline__ void operator()(const f32x4 (&acc)[2][2][4][2], const pg8::Unit& u, int wr, int wc, int fr_, int fq_) const {
;     ...
;                 const int lr = lrow0 + ai * 128 + m * 16;
;                 const float rs = rs8[ai * 4 + m];
;                 const f32x4 g0 = acc[ai][0][m][0] * rs + sv[0][0], g1 = acc[ai][0][m][1] * rs + sv[0][1];
;                 const f32x4 u0 = acc[ai][1][m][0] * rs + sv[1][0], u1 = acc[ai][1][m][1] * rs + sv[1][1];
;                 const f32x2 ha = pg8::silu_mul_pk((f32x2){g0[0], g0[1]}, (f32x2){u0[0], u0[1]}), hb = pg8::silu_mul_pk((f32x2){g0[2], g0[3]}, (f32x2){u0[2], u0[3]});
;                 const f32x2 hc = pg8::silu_mul_pk((f32x2){g1[0], g1[1]}, (f32x2){u1[0], u1[1]}), hd = pg8::silu_mul_pk((f32x2){g1[2], g1[3]}, (f32x2){u1[2], u1[3]});
;                 u32x4 w; w.x = cvt_pk_bf16(ha.x, ha.y); w.y = cvt_pk_bf16(hb.x, hb.y); w.z = cvt_pk_bf16(hc.x, hc.y); w.w = cvt_pk_bf16(hd.x, hd.y);
;                 *(u32x4*)(H + (size_t)lr * FF + hcol) = w;
	v_mad_i64_i32 v[136:137], s[26:27], v165, s2, v[128:129]
	v_lshlrev_b64 v[130:131], 1, v[174:175]
	v_lshl_add_u64 v[136:137], v[136:137], 0, v[130:131]
	global_store_dwordx4 v[136:137], v[132:135], off
	v_pk_fma_f32 v[66:67], v[66:67], v[166:167], v[82:83] op_sel_hi:[1,0,1]
	v_pk_fma_f32 v[62:63], v[62:63], v[164:165], v[94:95] op_sel_hi:[1,0,1]
	v_pk_mul_f32 v[132:133], v[124:125], s[88:89] op_sel_hi:[1,0]
	v_pk_mul_f32 v[124:125], v[126:127], s[88:89] op_sel_hi:[1,0]
	v_exp_f32_e32 v132, v132
	v_exp_f32_e32 v124, v124
	v_exp_f32_e32 v125, v125
	v_exp_f32_e32 v133, v133
	v_or_b32_e32 v134, 16, v165
	v_pk_mul_f32 v[66:67], v[74:75], v[66:67]
	v_pk_add_f32 v[124:125], v[124:125], 1.0 op_sel_hi:[1,0]
	v_pk_add_f32 v[132:133], v[132:133], 1.0 op_sel_hi:[1,0]
	v_rcp_f32_e32 v124, v124
	v_rcp_f32_e32 v125, v125
	v_rcp_f32_e32 v132, v132
	v_rcp_f32_e32 v133, v133
	v_pk_fma_f32 v[60:61], v[60:61], v[164:165], v[92:93] op_sel_hi:[1,0,1]
	v_pk_mul_f32 v[118:119], v[118:119], v[124:125]
	v_pk_mul_f32 v[124:125], v[120:121], s[88:89] op_sel_hi:[1,0]
	v_pk_mul_f32 v[116:117], v[116:117], v[132:133]
	v_exp_f32_e32 v124, v124
	v_exp_f32_e32 v125, v125
	v_pk_fma_f32 v[52:53], v[52:53], v[164:165], v[84:85] op_sel_hi:[1,0,1]
	v_pk_fma_f32 v[54:55], v[54:55], v[164:165], v[86:87] op_sel_hi:[1,0,1]
	v_pk_mul_f32 v[52:53], v[60:61], v[52:53]
	v_pk_add_f32 v[124:125], v[124:125], 1.0 op_sel_hi:[1,0]
	v_pk_fma_f32 v[56:57], v[56:57], v[164:165], v[88:89] op_sel_hi:[1,0,1]
	v_rcp_f32_e32 v124, v124
	v_rcp_f32_e32 v125, v125
	v_pk_mul_f32 v[54:55], v[62:63], v[54:55]
	v_pk_fma_f32 v[48:49], v[48:49], v[164:165], v[80:81] op_sel_hi:[1,0,1]
	v_pk_fma_f32 v[58:59], v[58:59], v[164:165], v[90:91] op_sel_hi:[1,0,1]
	v_pk_mul_f32 v[120:121], v[112:113], v[124:125]
	v_pk_mul_f32 v[112:113], v[122:123], s[88:89] op_sel_hi:[1,0]
	v_pk_mul_f32 v[48:49], v[56:57], v[48:49]
	v_exp_f32_e32 v112, v112
	v_exp_f32_e32 v113, v113
	v_pk_fma_f32 v[50:51], v[50:51], v[164:165], v[82:83] op_sel_hi:[1,0,1]
	v_pk_fma_f32 v[46:47], v[46:47], v[162:163], v[94:95] op_sel_hi:[1,0,1]
	v_pk_mul_f32 v[50:51], v[58:59], v[50:51]
	v_pk_add_f32 v[112:113], v[112:113], 1.0 op_sel_hi:[1,0]
	v_pk_fma_f32 v[44:45], v[44:45], v[162:163], v[92:93] op_sel_hi:[1,0,1]
	v_rcp_f32_e32 v112, v112
	v_rcp_f32_e32 v113, v113
	v_pk_fma_f32 v[36:37], v[36:37], v[162:163], v[84:85] op_sel_hi:[1,0,1]
	v_pk_fma_f32 v[38:39], v[38:39], v[162:163], v[86:87] op_sel_hi:[1,0,1]
	v_pk_mul_f32 v[36:37], v[44:45], v[36:37]
	v_pk_mul_f32 v[122:123], v[114:115], v[112:113]
	v_cvt_pk_bf16_f32 v112, v116, v117
	v_mad_i64_i32 v[116:117], s[26:27], v134, s2, v[128:129]
	v_cvt_pk_bf16_f32 v113, v118, v119
	v_lshl_add_u64 v[116:117], v[116:117], 0, v[130:131]
	v_cvt_pk_bf16_f32 v114, v120, v121
	v_cvt_pk_bf16_f32 v115, v122, v123
	global_store_dwordx4 v[116:117], v[112:115], off
	v_pk_fma_f32 v[40:41], v[40:41], v[162:163], v[88:89] op_sel_hi:[1,0,1]
	v_pk_mul_f32 v[38:39], v[46:47], v[38:39]
	v_pk_mul_f32 v[112:113], v[108:109], s[88:89] op_sel_hi:[1,0]
	v_pk_mul_f32 v[108:109], v[110:111], s[88:89] op_sel_hi:[1,0]
	v_exp_f32_e32 v112, v112
	v_exp_f32_e32 v108, v108
	v_exp_f32_e32 v109, v109
	v_exp_f32_e32 v113, v113
	v_or_b32_e32 v114, 32, v165
	v_pk_fma_f32 v[32:33], v[32:33], v[162:163], v[80:81] op_sel_hi:[1,0,1]
	v_pk_add_f32 v[108:109], v[108:109], 1.0 op_sel_hi:[1,0]
	v_pk_add_f32 v[112:113], v[112:113], 1.0 op_sel_hi:[1,0]
	v_rcp_f32_e32 v108, v108
	v_rcp_f32_e32 v109, v109
	v_rcp_f32_e32 v112, v112
	v_rcp_f32_e32 v113, v113
	v_pk_fma_f32 v[42:43], v[42:43], v[162:163], v[90:91] op_sel_hi:[1,0,1]
	v_pk_mul_f32 v[102:103], v[102:103], v[108:109]
	v_pk_mul_f32 v[108:109], v[104:105], s[88:89] op_sel_hi:[1,0]
	v_pk_mul_f32 v[100:101], v[100:101], v[112:113]
	v_exp_f32_e32 v108, v108
	v_exp_f32_e32 v109, v109
	v_pk_mul_f32 v[32:33], v[40:41], v[32:33]
	v_pk_add_f32 v[108:109], v[108:109], 1.0 op_sel_hi:[1,0]
	v_pk_fma_f32 v[34:35], v[34:35], v[162:163], v[82:83] op_sel_hi:[1,0,1]
	v_rcp_f32_e32 v108, v108
	v_rcp_f32_e32 v109, v109
	v_pk_mul_f32 v[34:35], v[42:43], v[34:35]
	v_pk_mul_f32 v[104:105], v[96:97], v[108:109]
	v_pk_mul_f32 v[96:97], v[106:107], s[88:89] op_sel_hi:[1,0]
	v_exp_f32_e32 v96, v96
	v_exp_f32_e32 v97, v97
	v_mov_b32_e32 v160, v214
	v_pk_fma_f32 v[30:31], v[30:31], v[160:161], v[94:95] op_sel_hi:[1,0,1]
	v_pk_fma_f32 v[28:29], v[28:29], v[160:161], v[92:93] op_sel_hi:[1,0,1]
	v_pk_add_f32 v[96:97], v[96:97], 1.0 op_sel_hi:[1,0]
	v_pk_fma_f32 v[20:21], v[20:21], v[160:161], v[84:85] op_sel_hi:[1,0,1]
	v_rcp_f32_e32 v96, v96
	v_rcp_f32_e32 v97, v97
	v_pk_mul_f32 v[20:21], v[28:29], v[20:21]
	v_pk_fma_f32 v[22:23], v[22:23], v[160:161], v[86:87] op_sel_hi:[1,0,1]
	v_pk_fma_f32 v[24:25], v[24:25], v[160:161], v[88:89] op_sel_hi:[1,0,1]
	v_pk_mul_f32 v[106:107], v[98:99], v[96:97]
	v_cvt_pk_bf16_f32 v96, v100, v101
	v_mad_i64_i32 v[100:101], s[26:27], v114, s2, v[128:129]
	v_cvt_pk_bf16_f32 v97, v102, v103
	v_lshl_add_u64 v[100:101], v[100:101], 0, v[130:131]
	v_cvt_pk_bf16_f32 v98, v104, v105
	v_cvt_pk_bf16_f32 v99, v106, v107
	global_store_dwordx4 v[100:101], v[96:99], off
	v_pk_mul_f32 v[22:23], v[30:31], v[22:23]
	v_pk_fma_f32 v[16:17], v[16:17], v[160:161], v[80:81] op_sel_hi:[1,0,1]
	v_pk_mul_f32 v[96:97], v[76:77], s[88:89] op_sel_hi:[1,0]
	v_pk_mul_f32 v[76:77], v[78:79], s[88:89] op_sel_hi:[1,0]
	v_exp_f32_e32 v96, v96
	v_exp_f32_e32 v76, v76
	v_exp_f32_e32 v77, v77
	v_exp_f32_e32 v97, v97
	v_or_b32_e32 v98, 48, v165
	v_pk_fma_f32 v[26:27], v[26:27], v[160:161], v[90:91] op_sel_hi:[1,0,1]
	v_pk_add_f32 v[76:77], v[76:77], 1.0 op_sel_hi:[1,0]
	v_pk_add_f32 v[96:97], v[96:97], 1.0 op_sel_hi:[1,0]
; __device__ __forceinline__ unsigned cvt_pk_bf16(float lo, float hi) { unsigned r; asm volatile("v_cvt_pk_bf16_f32 %0, %1, %2" : "=v"(r) : "v"(lo), "v"(hi)); return r; }
;     __device__ __forceinline__ void operator()(const f32x4 (&acc)[2][2][4][2], const pg8::Unit& u, int wr, int wc, int fr_, int fq_) const {
;     ...
;                 const int lr = lrow0 + ai * 128 + m * 16;
;                 const float rs = rs8[ai * 4 + m];
;                 const f32x4 g0 = acc[ai][0][m][0] * rs + sv[0][0], g1 = acc[ai][0][m][1] * rs + sv[0][1];
;                 const f32x4 u0 = acc[ai][1][m][0] * rs + sv[1][0], u1 = acc[ai][1][m][1] * rs + sv[1][1];
;                 const f32x2 ha = pg8::silu_mul_pk((f32x2){g0[0], g0[1]}, (f32x2){u0[0], u0[1]}), hb = pg8::silu_mul_pk((f32x2){g0[2], g0[3]}, (f32x2){u0[2], u0[3]});
;                 const f32x2 hc = pg8::silu_mul_pk((f32x2){g1[0], g1[1]}, (f32x2){u1[0], u1[1]}), hd = pg8::silu_mul_pk((f32x2){g1[2], g1[3]}, (f32x2){u1[2], u1[3]});
;                 u32x4 w; w.x = cvt_pk_bf16(ha.x, ha.y); w.y = cvt_pk_bf16(hb.x, hb.y); w.z = cvt_pk_bf16(hc.x, hc.y); w.w = cvt_pk_bf16(hd.x, hd.y);
;                 *(u32x4*)(H + (size_t)lr * FF + hcol) = w;
	v_rcp_f32_e32 v76, v76
	v_rcp_f32_e32 v77, v77
	v_rcp_f32_e32 v96, v96
	v_rcp_f32_e32 v97, v97
	v_pk_mul_f32 v[16:17], v[24:25], v[16:17]
	v_pk_mul_f32 v[70:71], v[70:71], v[76:77]
	v_pk_mul_f32 v[76:77], v[72:73], s[88:89] op_sel_hi:[1,0]
	v_pk_mul_f32 v[68:69], v[68:69], v[96:97]
	v_exp_f32_e32 v76, v76
	v_exp_f32_e32 v77, v77
	v_pk_fma_f32 v[18:19], v[18:19], v[160:161], v[82:83] op_sel_hi:[1,0,1]
	v_pk_add_f32 v[76:77], v[76:77], 1.0 op_sel_hi:[1,0]
	v_rcp_f32_e32 v76, v76
	v_rcp_f32_e32 v77, v77
	v_pk_mul_f32 v[18:19], v[26:27], v[18:19]
	v_pk_mul_f32 v[72:73], v[64:65], v[76:77]
	v_pk_mul_f32 v[64:65], v[74:75], s[88:89] op_sel_hi:[1,0]
	v_exp_f32_e32 v64, v64
	v_exp_f32_e32 v65, v65
	v_mov_b32_e32 v158, v215
	v_pk_fma_f32 v[14:15], v[14:15], v[158:159], v[94:95] op_sel_hi:[1,0,1]
	v_pk_fma_f32 v[12:13], v[12:13], v[158:159], v[92:93] op_sel_hi:[1,0,1]
	v_pk_add_f32 v[64:65], v[64:65], 1.0 op_sel_hi:[1,0]
	v_pk_fma_f32 v[4:5], v[4:5], v[158:159], v[84:85] op_sel_hi:[1,0,1]
	v_rcp_f32_e32 v64, v64
	v_rcp_f32_e32 v65, v65
	v_pk_mul_f32 v[4:5], v[12:13], v[4:5]
	v_pk_fma_f32 v[6:7], v[6:7], v[158:159], v[86:87] op_sel_hi:[1,0,1]
	v_pk_fma_f32 v[8:9], v[8:9], v[158:159], v[88:89] op_sel_hi:[1,0,1]
	v_pk_mul_f32 v[74:75], v[66:67], v[64:65]
	v_cvt_pk_bf16_f32 v64, v68, v69
	v_mad_i64_i32 v[68:69], s[26:27], v98, s2, v[128:129]
	v_cvt_pk_bf16_f32 v65, v70, v71
	v_lshl_add_u64 v[68:69], v[68:69], 0, v[130:131]
	v_cvt_pk_bf16_f32 v66, v72, v73
	v_cvt_pk_bf16_f32 v67, v74, v75
	global_store_dwordx4 v[68:69], v[64:67], off
	v_pk_mul_f32 v[6:7], v[14:15], v[6:7]
	v_pk_fma_f32 v[0:1], v[0:1], v[158:159], v[80:81] op_sel_hi:[1,0,1]
	v_pk_mul_f32 v[64:65], v[60:61], s[88:89] op_sel_hi:[1,0]
	v_pk_mul_f32 v[60:61], v[62:63], s[88:89] op_sel_hi:[1,0]
	v_exp_f32_e32 v64, v64
	v_exp_f32_e32 v60, v60
	v_exp_f32_e32 v61, v61
	v_exp_f32_e32 v65, v65
	v_add_u32_e32 v66, 0x80, v165
	v_pk_fma_f32 v[10:11], v[10:11], v[158:159], v[90:91] op_sel_hi:[1,0,1]
	v_pk_add_f32 v[60:61], v[60:61], 1.0 op_sel_hi:[1,0]
	v_pk_add_f32 v[64:65], v[64:65], 1.0 op_sel_hi:[1,0]
	v_rcp_f32_e32 v60, v60
	v_rcp_f32_e32 v61, v61
	v_rcp_f32_e32 v64, v64
	v_rcp_f32_e32 v65, v65
	v_pk_mul_f32 v[0:1], v[8:9], v[0:1]
	v_pk_mul_f32 v[54:55], v[54:55], v[60:61]
	v_pk_mul_f32 v[60:61], v[56:57], s[88:89] op_sel_hi:[1,0]
	v_pk_mul_f32 v[52:53], v[52:53], v[64:65]
	v_exp_f32_e32 v60, v60
	v_exp_f32_e32 v61, v61
	v_pk_fma_f32 v[2:3], v[2:3], v[158:159], v[82:83] op_sel_hi:[1,0,1]
	s_andn2_b64 vcc, exec, s[36:37]
	v_pk_mul_f32 v[2:3], v[10:11], v[2:3]
	v_pk_add_f32 v[60:61], v[60:61], 1.0 op_sel_hi:[1,0]
	s_nop 0
	v_rcp_f32_e32 v60, v60
	v_rcp_f32_e32 v61, v61
	s_nop 0
	v_pk_mul_f32 v[56:57], v[48:49], v[60:61]
	v_pk_mul_f32 v[48:49], v[58:59], s[88:89] op_sel_hi:[1,0]
	s_nop 0
	v_exp_f32_e32 v48, v48
	v_exp_f32_e32 v49, v49
	s_nop 0
	v_pk_add_f32 v[48:49], v[48:49], 1.0 op_sel_hi:[1,0]
	s_nop 0
	v_rcp_f32_e32 v48, v48
	v_rcp_f32_e32 v49, v49
	s_nop 0
	v_pk_mul_f32 v[58:59], v[50:51], v[48:49]
	v_cvt_pk_bf16_f32 v48, v52, v53
	v_mad_i64_i32 v[52:53], s[26:27], v66, s2, v[128:129]
	v_cvt_pk_bf16_f32 v49, v54, v55
	v_lshl_add_u64 v[52:53], v[52:53], 0, v[130:131]
	v_cvt_pk_bf16_f32 v50, v56, v57
	v_cvt_pk_bf16_f32 v51, v58, v59
	global_store_dwordx4 v[52:53], v[48:51], off
	s_nop 1
	v_pk_mul_f32 v[48:49], v[44:45], s[88:89] op_sel_hi:[1,0]
	v_pk_mul_f32 v[44:45], v[46:47], s[88:89] op_sel_hi:[1,0]
	v_exp_f32_e32 v48, v48
	v_exp_f32_e32 v44, v44
	v_exp_f32_e32 v45, v45
	v_exp_f32_e32 v49, v49
	v_add_u32_e32 v50, 0x90, v165
	v_pk_add_f32 v[44:45], v[44:45], 1.0 op_sel_hi:[1,0]
	s_nop 0
	v_rcp_f32_e32 v44, v44
	v_rcp_f32_e32 v45, v45
	v_pk_add_f32 v[48:49], v[48:49], 1.0 op_sel_hi:[1,0]
	v_pk_mul_f32 v[38:39], v[38:39], v[44:45]
; __device__ __forceinline__ unsigned cvt_pk_bf16(float lo, float hi) { unsigned r; asm volatile("v_cvt_pk_bf16_f32 %0, %1, %2" : "=v"(r) : "v"(lo), "v"(hi)); return r; }
; template <class Epi, class Sched, bool ALIGN_EPI, bool SP2>
; __device__ __forceinline__ void gemm_phase(PG8_LAS unsigned char* lds, const Gemm g, const Sched& S, const Epi& E, int wid) {
;     ...
;         if (!has_next) break;
;     __device__ __forceinline__ void operator()(const f32x4 (&acc)[2][2][4][2], const pg8::Unit& u, int wr, int wc, int fr_, int fq_) const {
;     ...
;                 const int lr = lrow0 + ai * 128 + m * 16;
;                 const float rs = rs8[ai * 4 + m];
;                 const f32x4 g0 = acc[ai][0][m][0] * rs + sv[0][0], g1 = acc[ai][0][m][1] * rs + sv[0][1];
;                 const f32x4 u0 = acc[ai][1][m][0] * rs + sv[1][0], u1 = acc[ai][1][m][1] * rs + sv[1][1];
;                 const f32x2 ha = pg8::silu_mul_pk((f32x2){g0[0], g0[1]}, (f32x2){u0[0], u0[1]}), hb = pg8::silu_mul_pk((f32x2){g0[2], g0[3]}, (f32x2){u0[2], u0[3]});
;                 const f32x2 hc = pg8::silu_mul_pk((f32x2){g1[0], g1[1]}, (f32x2){u1[0], u1[1]}), hd = pg8::silu_mul_pk((f32x2){g1[2], g1[3]}, (f32x2){u1[2], u1[3]});
;                 u32x4 w; w.x = cvt_pk_bf16(ha.x, ha.y); w.y = cvt_pk_bf16(hb.x, hb.y); w.z = cvt_pk_bf16(hc.x, hc.y); w.w = cvt_pk_bf16(hd.x, hd.y);
;                 *(u32x4*)(H + (size_t)lr * FF + hcol) = w;
	v_pk_mul_f32 v[44:45], v[40:41], s[88:89] op_sel_hi:[1,0]
	v_rcp_f32_e32 v48, v48
	v_exp_f32_e32 v44, v44
	v_exp_f32_e32 v45, v45
	v_rcp_f32_e32 v49, v49
	v_pk_add_f32 v[44:45], v[44:45], 1.0 op_sel_hi:[1,0]
	s_nop 0
	v_rcp_f32_e32 v44, v44
	v_rcp_f32_e32 v45, v45
	v_pk_mul_f32 v[36:37], v[36:37], v[48:49]
	v_pk_mul_f32 v[40:41], v[32:33], v[44:45]
	v_pk_mul_f32 v[32:33], v[42:43], s[88:89] op_sel_hi:[1,0]
	s_nop 0
	v_exp_f32_e32 v32, v32
	v_exp_f32_e32 v33, v33
	s_nop 0
	v_pk_add_f32 v[32:33], v[32:33], 1.0 op_sel_hi:[1,0]
	s_nop 0
	v_rcp_f32_e32 v32, v32
	v_rcp_f32_e32 v33, v33
	s_nop 0
	v_pk_mul_f32 v[42:43], v[34:35], v[32:33]
	v_cvt_pk_bf16_f32 v32, v36, v37
	v_mad_i64_i32 v[36:37], s[26:27], v50, s2, v[128:129]
	v_cvt_pk_bf16_f32 v33, v38, v39
	v_lshl_add_u64 v[36:37], v[36:37], 0, v[130:131]
	v_cvt_pk_bf16_f32 v34, v40, v41
	v_cvt_pk_bf16_f32 v35, v42, v43
	global_store_dwordx4 v[36:37], v[32:35], off
	s_nop 1
	v_pk_mul_f32 v[32:33], v[28:29], s[88:89] op_sel_hi:[1,0]
	v_pk_mul_f32 v[28:29], v[30:31], s[88:89] op_sel_hi:[1,0]
	v_exp_f32_e32 v32, v32
	v_exp_f32_e32 v28, v28
	v_exp_f32_e32 v29, v29
	v_exp_f32_e32 v33, v33
	v_add_u32_e32 v34, 0xa0, v165
	v_pk_add_f32 v[28:29], v[28:29], 1.0 op_sel_hi:[1,0]
	s_nop 0
	v_rcp_f32_e32 v28, v28
	v_rcp_f32_e32 v29, v29
	v_pk_add_f32 v[32:33], v[32:33], 1.0 op_sel_hi:[1,0]
	v_pk_mul_f32 v[22:23], v[22:23], v[28:29]
	v_pk_mul_f32 v[28:29], v[24:25], s[88:89] op_sel_hi:[1,0]
	v_rcp_f32_e32 v32, v32
	v_exp_f32_e32 v28, v28
	v_exp_f32_e32 v29, v29
	v_rcp_f32_e32 v33, v33
	v_pk_add_f32 v[28:29], v[28:29], 1.0 op_sel_hi:[1,0]
	s_nop 0
	v_rcp_f32_e32 v28, v28
	v_rcp_f32_e32 v29, v29
	v_pk_mul_f32 v[20:21], v[20:21], v[32:33]
	v_pk_mul_f32 v[24:25], v[16:17], v[28:29]
	v_pk_mul_f32 v[16:17], v[26:27], s[88:89] op_sel_hi:[1,0]
	s_nop 0
	v_exp_f32_e32 v16, v16
	v_exp_f32_e32 v17, v17
	s_nop 0
	v_pk_add_f32 v[16:17], v[16:17], 1.0 op_sel_hi:[1,0]
	s_nop 0
	v_rcp_f32_e32 v16, v16
	v_rcp_f32_e32 v17, v17
	s_nop 0
	v_pk_mul_f32 v[26:27], v[18:19], v[16:17]
	v_cvt_pk_bf16_f32 v16, v20, v21
	v_mad_i64_i32 v[20:21], s[26:27], v34, s2, v[128:129]
	v_cvt_pk_bf16_f32 v17, v22, v23
	v_lshl_add_u64 v[20:21], v[20:21], 0, v[130:131]
	v_cvt_pk_bf16_f32 v18, v24, v25
	v_cvt_pk_bf16_f32 v19, v26, v27
	global_store_dwordx4 v[20:21], v[16:19], off
	s_nop 1
	v_pk_mul_f32 v[16:17], v[12:13], s[88:89] op_sel_hi:[1,0]
	v_pk_mul_f32 v[12:13], v[14:15], s[88:89] op_sel_hi:[1,0]
	v_exp_f32_e32 v16, v16
	v_exp_f32_e32 v12, v12
	v_exp_f32_e32 v13, v13
	v_exp_f32_e32 v17, v17
	v_add_u32_e32 v18, 0xb0, v165
	v_pk_add_f32 v[12:13], v[12:13], 1.0 op_sel_hi:[1,0]
	s_nop 0
	v_rcp_f32_e32 v12, v12
	v_rcp_f32_e32 v13, v13
	v_pk_add_f32 v[16:17], v[16:17], 1.0 op_sel_hi:[1,0]
	v_pk_mul_f32 v[6:7], v[6:7], v[12:13]
	v_pk_mul_f32 v[12:13], v[8:9], s[88:89] op_sel_hi:[1,0]
	v_rcp_f32_e32 v16, v16
	v_exp_f32_e32 v12, v12
	v_exp_f32_e32 v13, v13
	v_rcp_f32_e32 v17, v17
	v_pk_add_f32 v[12:13], v[12:13], 1.0 op_sel_hi:[1,0]
	s_nop 0
	v_rcp_f32_e32 v12, v12
	v_rcp_f32_e32 v13, v13
	v_pk_mul_f32 v[4:5], v[4:5], v[16:17]
	v_pk_mul_f32 v[8:9], v[0:1], v[12:13]
	v_pk_mul_f32 v[0:1], v[10:11], s[88:89] op_sel_hi:[1,0]
	s_nop 0
	v_exp_f32_e32 v0, v0
	v_exp_f32_e32 v1, v1
	s_nop 0
	v_pk_add_f32 v[0:1], v[0:1], 1.0 op_sel_hi:[1,0]
	s_nop 0
	v_rcp_f32_e32 v0, v0
	v_rcp_f32_e32 v1, v1
	s_nop 0
	v_pk_mul_f32 v[10:11], v[2:3], v[0:1]
	v_cvt_pk_bf16_f32 v0, v4, v5
	v_mad_i64_i32 v[4:5], s[26:27], v18, s2, v[128:129]
	v_lshl_add_u64 v[4:5], v[4:5], 0, v[130:131]
	s_mov_b64 s[26:27], -1
	v_cvt_pk_bf16_f32 v1, v6, v7
	v_cvt_pk_bf16_f32 v2, v8, v9
	v_cvt_pk_bf16_f32 v3, v10, v11
	global_store_dwordx4 v[4:5], v[0:3], off
	s_cbranch_vccnz .LBB0_369
	s_and_b64 vcc, exec, s[34:35]
	s_cbranch_vccnz .LBB0_368
	s_branch .LBB0_368
